# sel: thread 0 publishes the next unit index during the radix stage, so the unit end has one barrier instead of two (no LDS write + second barrier on the unit-to-unit path)
# speedup vs baseline: 1.0030x; 1.0030x over previous
.Lsel_next:
	ds_read_b32 v0, v0
	s_waitcnt lgkmcnt(0)
	v_readfirstlane_b32 s12, v0
	s_cmpk_lt_i32 s12, 0x2040
	s_cbranch_scc0 .LBB0_1143

.LBB0_843:
	s_and_saveexec_b64 s[100:101], s[28:29]
	s_cbranch_execz .Lnid_skip
	s_waitcnt vmcnt(0)
	v_mov_b32_e32 v248, s3
	ds_write_b32 v248, v240
.Lnid_skip:
	s_or_b64 exec, exec, s[100:101]
	s_lshl_b32 s6, s12, 10
	s_add_i32 s40, s6, 0
	s_add_i32 s40, s40, 0x20000
	s_add_i32 s41, s41, s12
	s_cmpk_gt_i32 s19, 0x100
	s_mov_b64 s[6:7], -1
	s_cbranch_scc0 .LBB0_1135
	v_xad_u32 v0, v99, 63, s19
	v_lshrrev_b32_e32 v1, 6, v0
	v_lshlrev_b32_e64 v2, v1, -1
	v_not_b32_e32 v2, v2
	v_cmp_gt_u32_e32 vcc, s49, v0
	v_subrev_u32_e32 v8, 32, v1
	v_lshlrev_b32_e64 v8, v8, -1
	v_cndmask_b32_e32 v7, -1, v2, vcc
	v_not_b32_e32 v8, v8
	v_cmp_lt_u32_e32 vcc, s50, v0
	v_subrev_u32_e32 v9, 64, v1
	v_lshlrev_b32_e64 v9, v9, -1
	v_cndmask_b32_e32 v8, 0, v8, vcc
	v_cmp_gt_u32_e32 vcc, s27, v0
	v_not_b32_e32 v9, v9
	v_add_u32_e32 v1, 0xffffffa0, v1
	v_cndmask_b32_e32 v6, -1, v8, vcc
	v_cmp_lt_u32_e32 vcc, s51, v0
	v_lshlrev_b32_e64 v1, v1, -1
	v_not_b32_e32 v1, v1
	v_cndmask_b32_e32 v9, 0, v9, vcc
	v_cmp_gt_u32_e32 vcc, s52, v0
	s_mov_b32 s57, 0
	v_mov_b32_e32 v3, 0
	v_cndmask_b32_e32 v5, -1, v9, vcc
	v_cmp_lt_u32_e32 vcc, s53, v0
	v_mov_b32_e32 v2, 0
	s_nop 0
	v_cndmask_b32_e32 v1, 0, v1, vcc
	v_cmp_gt_u32_e32 vcc, s48, v0
	v_mov_b32_e32 v0, 0
	s_nop 0
	v_cndmask_b32_e32 v4, -1, v1, vcc
	v_mov_b32_e32 v1, 0
	s_cmpk_gt_u32 s19, 0x1800
	s_cbranch_scc1 .Lrdx_w4
	s_cmpk_gt_u32 s19, 0x1000
	s_cbranch_scc1 .Lrdx_w3
	s_cmpk_gt_u32 s19, 0x800
	s_cbranch_scc1 .Lrdx_w2
	v_mov_b32_e32 v9, 0
	v_mov_b32_e32 v10, 0
	v_mov_b32_e32 v11, 0
	s_mov_b32 s58, -1
	v_bitop3_b32 v8, v7, v189, s58 bitop3:0x60
	v_bcnt_u32_b32 v12, v8, 0
	s_nop 1
	v_add_u32_dpp v12, v12, v12 row_ror:8 row_mask:0xf bank_mask:0xf bound_ctrl:1
	s_nop 1
	v_add_u32_dpp v12, v12, v12 row_ror:4 row_mask:0xf bank_mask:0xf bound_ctrl:1
	s_nop 1
	v_add_u32_dpp v12, v12, v12 row_ror:2 row_mask:0xf bank_mask:0xf bound_ctrl:1
	s_nop 1
	v_add_u32_dpp v12, v12, v12 row_ror:1 row_mask:0xf bank_mask:0xf bound_ctrl:1
	s_nop 0
	v_readlane_b32 s6, v12, 0
	v_readlane_b32 s7, v12, 16
	v_readlane_b32 s8, v12, 32
	v_readlane_b32 s9, v12, 48
	s_add_i32 s6, s6, s7
	s_add_i32 s8, s8, s9
	s_add_i32 s6, s6, s57
	s_add_i32 s8, s6, s8
	s_cmpk_eq_i32 s8, 0x100
	s_cbranch_scc1 .Lrdx_eq
	s_cmpk_lt_i32 s8, 0x100
	s_cselect_b32 s6, -1, 0
	s_cselect_b32 s57, s8, s57
	s_xor_b32 s59, s58, s6
	v_bitop3_b32 v7, v7, v189, s59 bitop3:0x60
	s_mov_b32 s58, s6
	v_bitop3_b32 v3, v3, v8, s6 bitop3:0xf8
	v_bitop3_b32 v8, v7, v188, s58 bitop3:0x60
	v_bcnt_u32_b32 v12, v8, 0
	s_nop 1
	v_add_u32_dpp v12, v12, v12 row_ror:8 row_mask:0xf bank_mask:0xf bound_ctrl:1
	s_nop 1
	v_add_u32_dpp v12, v12, v12 row_ror:4 row_mask:0xf bank_mask:0xf bound_ctrl:1
	s_nop 1
	v_add_u32_dpp v12, v12, v12 row_ror:2 row_mask:0xf bank_mask:0xf bound_ctrl:1
	s_nop 1
	v_add_u32_dpp v12, v12, v12 row_ror:1 row_mask:0xf bank_mask:0xf bound_ctrl:1
	s_nop 0
	v_readlane_b32 s6, v12, 0
	v_readlane_b32 s7, v12, 16
	v_readlane_b32 s8, v12, 32
	v_readlane_b32 s9, v12, 48
	s_add_i32 s6, s6, s7
	s_add_i32 s8, s8, s9
	s_add_i32 s6, s6, s57
	s_add_i32 s8, s6, s8
	s_cmpk_eq_i32 s8, 0x100
	s_cbranch_scc1 .Lrdx_eq
	s_cmpk_lt_i32 s8, 0x100
	s_cselect_b32 s6, -1, 0
	s_cselect_b32 s57, s8, s57
	s_xor_b32 s59, s58, s6
	v_bitop3_b32 v7, v7, v188, s59 bitop3:0x60
	v_bitop3_b32 v3, v3, v8, s6 bitop3:0xf8
	v_bitop3_b32 v8, v7, v187, s58 bitop3:0x60
	v_bcnt_u32_b32 v12, v8, 0
	s_nop 1
	v_add_u32_dpp v12, v12, v12 row_ror:8 row_mask:0xf bank_mask:0xf bound_ctrl:1
	s_nop 1
	v_add_u32_dpp v12, v12, v12 row_ror:4 row_mask:0xf bank_mask:0xf bound_ctrl:1
	s_nop 1
	v_add_u32_dpp v12, v12, v12 row_ror:2 row_mask:0xf bank_mask:0xf bound_ctrl:1
	s_nop 1
	v_add_u32_dpp v12, v12, v12 row_ror:1 row_mask:0xf bank_mask:0xf bound_ctrl:1
	s_nop 0
	v_readlane_b32 s6, v12, 0
	v_readlane_b32 s7, v12, 16
	v_readlane_b32 s8, v12, 32
	v_readlane_b32 s9, v12, 48
	s_add_i32 s6, s6, s7
	s_add_i32 s8, s8, s9
	s_add_i32 s6, s6, s57
	s_add_i32 s8, s6, s8
	s_cmpk_eq_i32 s8, 0x100
	s_cbranch_scc1 .Lrdx_eq
	s_cmpk_lt_i32 s8, 0x100
	s_cselect_b32 s6, -1, 0
	s_cselect_b32 s57, s8, s57
	s_xor_b32 s59, s58, s6
	v_bitop3_b32 v7, v7, v187, s59 bitop3:0x60
	v_bitop3_b32 v3, v3, v8, s6 bitop3:0xf8
	v_bitop3_b32 v8, v7, v184, s58 bitop3:0x60
	v_bcnt_u32_b32 v12, v8, 0
	s_nop 1
	v_add_u32_dpp v12, v12, v12 row_ror:8 row_mask:0xf bank_mask:0xf bound_ctrl:1
	s_nop 1
	v_add_u32_dpp v12, v12, v12 row_ror:4 row_mask:0xf bank_mask:0xf bound_ctrl:1
	s_nop 1
	v_add_u32_dpp v12, v12, v12 row_ror:2 row_mask:0xf bank_mask:0xf bound_ctrl:1
	s_nop 1
	v_add_u32_dpp v12, v12, v12 row_ror:1 row_mask:0xf bank_mask:0xf bound_ctrl:1
	s_nop 0
	v_readlane_b32 s6, v12, 0
	v_readlane_b32 s7, v12, 16
	v_readlane_b32 s8, v12, 32
	v_readlane_b32 s9, v12, 48
	s_add_i32 s6, s6, s7
	s_add_i32 s8, s8, s9
	s_add_i32 s6, s6, s57
	s_add_i32 s8, s6, s8
	s_cmpk_eq_i32 s8, 0x100
	s_cbranch_scc1 .Lrdx_eq
	s_cmpk_lt_i32 s8, 0x100
	s_cselect_b32 s6, -1, 0
	s_cselect_b32 s57, s8, s57
	s_xor_b32 s59, s58, s6
	v_bitop3_b32 v7, v7, v184, s59 bitop3:0x60
	v_bitop3_b32 v3, v3, v8, s6 bitop3:0xf8
	v_bitop3_b32 v8, v7, v181, s58 bitop3:0x60
	v_bcnt_u32_b32 v12, v8, 0
	s_nop 1
	v_add_u32_dpp v12, v12, v12 row_ror:8 row_mask:0xf bank_mask:0xf bound_ctrl:1
	s_nop 1
	v_add_u32_dpp v12, v12, v12 row_ror:4 row_mask:0xf bank_mask:0xf bound_ctrl:1
	s_nop 1
	v_add_u32_dpp v12, v12, v12 row_ror:2 row_mask:0xf bank_mask:0xf bound_ctrl:1
	s_nop 1
	v_add_u32_dpp v12, v12, v12 row_ror:1 row_mask:0xf bank_mask:0xf bound_ctrl:1
	s_nop 0
	v_readlane_b32 s6, v12, 0
	v_readlane_b32 s7, v12, 16
	v_readlane_b32 s8, v12, 32
	v_readlane_b32 s9, v12, 48
	s_add_i32 s6, s6, s7
	s_add_i32 s8, s8, s9
	s_add_i32 s6, s6, s57
	s_add_i32 s8, s6, s8
	s_cmpk_eq_i32 s8, 0x100
	s_cbranch_scc1 .Lrdx_eq
	s_cmpk_lt_i32 s8, 0x100
	s_cselect_b32 s6, -1, 0
	s_cselect_b32 s57, s8, s57
	s_xor_b32 s59, s58, s6
	v_bitop3_b32 v7, v7, v181, s59 bitop3:0x60
	v_bitop3_b32 v3, v3, v8, s6 bitop3:0xf8
	v_bitop3_b32 v8, v7, v160, s58 bitop3:0x60
	v_bcnt_u32_b32 v12, v8, 0
	s_nop 1
	v_add_u32_dpp v12, v12, v12 row_ror:8 row_mask:0xf bank_mask:0xf bound_ctrl:1
	s_nop 1
	v_add_u32_dpp v12, v12, v12 row_ror:4 row_mask:0xf bank_mask:0xf bound_ctrl:1
	s_nop 1
	v_add_u32_dpp v12, v12, v12 row_ror:2 row_mask:0xf bank_mask:0xf bound_ctrl:1
	s_nop 1
	v_add_u32_dpp v12, v12, v12 row_ror:1 row_mask:0xf bank_mask:0xf bound_ctrl:1
	s_nop 0
	v_readlane_b32 s6, v12, 0
	v_readlane_b32 s7, v12, 16
	v_readlane_b32 s8, v12, 32
	v_readlane_b32 s9, v12, 48
	s_add_i32 s6, s6, s7
	s_add_i32 s8, s8, s9
	s_add_i32 s6, s6, s57
	s_add_i32 s8, s6, s8
	s_cmpk_eq_i32 s8, 0x100
	s_cbranch_scc1 .Lrdx_eq
	s_cmpk_lt_i32 s8, 0x100
	s_cselect_b32 s6, -1, 0
	s_cselect_b32 s57, s8, s57
	s_xor_b32 s59, s58, s6
	v_bitop3_b32 v7, v7, v160, s59 bitop3:0x60
	v_bitop3_b32 v3, v3, v8, s6 bitop3:0xf8
	v_bitop3_b32 v8, v7, v158, s58 bitop3:0x60
	v_bcnt_u32_b32 v12, v8, 0
	s_nop 1
	v_add_u32_dpp v12, v12, v12 row_ror:8 row_mask:0xf bank_mask:0xf bound_ctrl:1
	s_nop 1
	v_add_u32_dpp v12, v12, v12 row_ror:4 row_mask:0xf bank_mask:0xf bound_ctrl:1
	s_nop 1
	v_add_u32_dpp v12, v12, v12 row_ror:2 row_mask:0xf bank_mask:0xf bound_ctrl:1
	s_nop 1
	v_add_u32_dpp v12, v12, v12 row_ror:1 row_mask:0xf bank_mask:0xf bound_ctrl:1
	s_nop 0
	v_readlane_b32 s6, v12, 0
	v_readlane_b32 s7, v12, 16
	v_readlane_b32 s8, v12, 32
	v_readlane_b32 s9, v12, 48
	s_add_i32 s6, s6, s7
	s_add_i32 s8, s8, s9
	s_add_i32 s6, s6, s57
	s_add_i32 s8, s6, s8
	s_cmpk_eq_i32 s8, 0x100
	s_cbranch_scc1 .Lrdx_eq
	s_cmpk_lt_i32 s8, 0x100
	s_cselect_b32 s6, -1, 0
	s_cselect_b32 s57, s8, s57
	s_xor_b32 s59, s58, s6
	v_bitop3_b32 v7, v7, v158, s59 bitop3:0x60
	v_bitop3_b32 v3, v3, v8, s6 bitop3:0xf8
	v_bitop3_b32 v8, v7, v156, s58 bitop3:0x60
	v_bcnt_u32_b32 v12, v8, 0
	s_nop 1
	v_add_u32_dpp v12, v12, v12 row_ror:8 row_mask:0xf bank_mask:0xf bound_ctrl:1
	s_nop 1
	v_add_u32_dpp v12, v12, v12 row_ror:4 row_mask:0xf bank_mask:0xf bound_ctrl:1
	s_nop 1
	v_add_u32_dpp v12, v12, v12 row_ror:2 row_mask:0xf bank_mask:0xf bound_ctrl:1
	s_nop 1
	v_add_u32_dpp v12, v12, v12 row_ror:1 row_mask:0xf bank_mask:0xf bound_ctrl:1
	s_nop 0
	v_readlane_b32 s6, v12, 0
	v_readlane_b32 s7, v12, 16
	v_readlane_b32 s8, v12, 32
	v_readlane_b32 s9, v12, 48
	s_add_i32 s6, s6, s7
	s_add_i32 s8, s8, s9
	s_add_i32 s6, s6, s57
	s_add_i32 s8, s6, s8
	s_cmpk_eq_i32 s8, 0x100
	s_cbranch_scc1 .Lrdx_eq
	s_cmpk_lt_i32 s8, 0x100
	s_cselect_b32 s6, -1, 0
	s_cselect_b32 s57, s8, s57
	s_xor_b32 s59, s58, s6
	v_bitop3_b32 v7, v7, v156, s59 bitop3:0x60
	v_bitop3_b32 v3, v3, v8, s6 bitop3:0xf8
	v_bitop3_b32 v8, v7, v154, s58 bitop3:0x60
	v_bcnt_u32_b32 v12, v8, 0
	s_nop 1
	v_add_u32_dpp v12, v12, v12 row_ror:8 row_mask:0xf bank_mask:0xf bound_ctrl:1
	s_nop 1
	v_add_u32_dpp v12, v12, v12 row_ror:4 row_mask:0xf bank_mask:0xf bound_ctrl:1
	s_nop 1
	v_add_u32_dpp v12, v12, v12 row_ror:2 row_mask:0xf bank_mask:0xf bound_ctrl:1
	s_nop 1
	v_add_u32_dpp v12, v12, v12 row_ror:1 row_mask:0xf bank_mask:0xf bound_ctrl:1
	s_nop 0
	v_readlane_b32 s6, v12, 0
	v_readlane_b32 s7, v12, 16
	v_readlane_b32 s8, v12, 32
	v_readlane_b32 s9, v12, 48
	s_add_i32 s6, s6, s7
	s_add_i32 s8, s8, s9
	s_add_i32 s6, s6, s57
	s_add_i32 s8, s6, s8
	s_cmpk_eq_i32 s8, 0x100
	s_cbranch_scc1 .Lrdx_eq
	s_cmpk_lt_i32 s8, 0x100
	s_cselect_b32 s6, -1, 0
	s_cselect_b32 s57, s8, s57
	s_xor_b32 s59, s58, s6
	v_bitop3_b32 v7, v7, v154, s59 bitop3:0x60
	v_bitop3_b32 v3, v3, v8, s6 bitop3:0xf8
	v_bitop3_b32 v8, v7, v152, s58 bitop3:0x60
	v_bcnt_u32_b32 v12, v8, 0
	s_nop 1
	v_add_u32_dpp v12, v12, v12 row_ror:8 row_mask:0xf bank_mask:0xf bound_ctrl:1
	s_nop 1
	v_add_u32_dpp v12, v12, v12 row_ror:4 row_mask:0xf bank_mask:0xf bound_ctrl:1
	s_nop 1
	v_add_u32_dpp v12, v12, v12 row_ror:2 row_mask:0xf bank_mask:0xf bound_ctrl:1
	s_nop 1
	v_add_u32_dpp v12, v12, v12 row_ror:1 row_mask:0xf bank_mask:0xf bound_ctrl:1
	s_nop 0
	v_readlane_b32 s6, v12, 0
	v_readlane_b32 s7, v12, 16
	v_readlane_b32 s8, v12, 32
	v_readlane_b32 s9, v12, 48
	s_add_i32 s6, s6, s7
	s_add_i32 s8, s8, s9
	s_add_i32 s6, s6, s57
	s_add_i32 s8, s6, s8
	s_cmpk_eq_i32 s8, 0x100
	s_cbranch_scc1 .Lrdx_eq
	s_cmpk_lt_i32 s8, 0x100
	s_cselect_b32 s6, -1, 0
	s_cselect_b32 s57, s8, s57
	s_xor_b32 s59, s58, s6
	v_bitop3_b32 v7, v7, v152, s59 bitop3:0x60
	v_bitop3_b32 v3, v3, v8, s6 bitop3:0xf8
	v_bitop3_b32 v8, v7, v150, s58 bitop3:0x60
	v_bcnt_u32_b32 v12, v8, 0
	s_nop 1
	v_add_u32_dpp v12, v12, v12 row_ror:8 row_mask:0xf bank_mask:0xf bound_ctrl:1
	s_nop 1
	v_add_u32_dpp v12, v12, v12 row_ror:4 row_mask:0xf bank_mask:0xf bound_ctrl:1
	s_nop 1
	v_add_u32_dpp v12, v12, v12 row_ror:2 row_mask:0xf bank_mask:0xf bound_ctrl:1
	s_nop 1
	v_add_u32_dpp v12, v12, v12 row_ror:1 row_mask:0xf bank_mask:0xf bound_ctrl:1
	s_nop 0
	v_readlane_b32 s6, v12, 0
	v_readlane_b32 s7, v12, 16
	v_readlane_b32 s8, v12, 32
	v_readlane_b32 s9, v12, 48
	s_add_i32 s6, s6, s7
	s_add_i32 s8, s8, s9
	s_add_i32 s6, s6, s57
	s_add_i32 s8, s6, s8
	s_cmpk_eq_i32 s8, 0x100
	s_cbranch_scc1 .Lrdx_eq
	s_cmpk_lt_i32 s8, 0x100
	s_cselect_b32 s6, -1, 0
	s_cselect_b32 s57, s8, s57
	s_xor_b32 s59, s58, s6
	v_bitop3_b32 v7, v7, v150, s59 bitop3:0x60
	v_bitop3_b32 v3, v3, v8, s6 bitop3:0xf8
	v_bitop3_b32 v8, v7, v148, s58 bitop3:0x60
	v_bcnt_u32_b32 v12, v8, 0
	s_nop 1
	v_add_u32_dpp v12, v12, v12 row_ror:8 row_mask:0xf bank_mask:0xf bound_ctrl:1
	s_nop 1
	v_add_u32_dpp v12, v12, v12 row_ror:4 row_mask:0xf bank_mask:0xf bound_ctrl:1
	s_nop 1
	v_add_u32_dpp v12, v12, v12 row_ror:2 row_mask:0xf bank_mask:0xf bound_ctrl:1
	s_nop 1
	v_add_u32_dpp v12, v12, v12 row_ror:1 row_mask:0xf bank_mask:0xf bound_ctrl:1
	s_nop 0
	v_readlane_b32 s6, v12, 0
	v_readlane_b32 s7, v12, 16
	v_readlane_b32 s8, v12, 32
	v_readlane_b32 s9, v12, 48
	s_add_i32 s6, s6, s7
	s_add_i32 s8, s8, s9
	s_add_i32 s6, s6, s57
	s_add_i32 s8, s6, s8
	s_cmpk_eq_i32 s8, 0x100
	s_cbranch_scc1 .Lrdx_eq
	s_cmpk_lt_i32 s8, 0x100
	s_cselect_b32 s6, -1, 0
	s_cselect_b32 s57, s8, s57
	s_xor_b32 s59, s58, s6
	v_bitop3_b32 v7, v7, v148, s59 bitop3:0x60
	v_bitop3_b32 v3, v3, v8, s6 bitop3:0xf8
	v_bitop3_b32 v8, v7, v146, s58 bitop3:0x60
	v_bcnt_u32_b32 v12, v8, 0
	s_nop 1
	v_add_u32_dpp v12, v12, v12 row_ror:8 row_mask:0xf bank_mask:0xf bound_ctrl:1
	s_nop 1
	v_add_u32_dpp v12, v12, v12 row_ror:4 row_mask:0xf bank_mask:0xf bound_ctrl:1
	s_nop 1
	v_add_u32_dpp v12, v12, v12 row_ror:2 row_mask:0xf bank_mask:0xf bound_ctrl:1
	s_nop 1
	v_add_u32_dpp v12, v12, v12 row_ror:1 row_mask:0xf bank_mask:0xf bound_ctrl:1
	s_nop 0
	v_readlane_b32 s6, v12, 0
	v_readlane_b32 s7, v12, 16
	v_readlane_b32 s8, v12, 32
	v_readlane_b32 s9, v12, 48
	s_add_i32 s6, s6, s7
	s_add_i32 s8, s8, s9
	s_add_i32 s6, s6, s57
	s_add_i32 s8, s6, s8
	s_cmpk_eq_i32 s8, 0x100
	s_cbranch_scc1 .Lrdx_eq
	s_cmpk_lt_i32 s8, 0x100
	s_cselect_b32 s6, -1, 0
	s_cselect_b32 s57, s8, s57
	s_xor_b32 s59, s58, s6
	v_bitop3_b32 v7, v7, v146, s59 bitop3:0x60
	v_bitop3_b32 v3, v3, v8, s6 bitop3:0xf8
	v_bitop3_b32 v8, v7, v144, s58 bitop3:0x60
	v_bcnt_u32_b32 v12, v8, 0
	s_nop 1
	v_add_u32_dpp v12, v12, v12 row_ror:8 row_mask:0xf bank_mask:0xf bound_ctrl:1
	s_nop 1
	v_add_u32_dpp v12, v12, v12 row_ror:4 row_mask:0xf bank_mask:0xf bound_ctrl:1
	s_nop 1
	v_add_u32_dpp v12, v12, v12 row_ror:2 row_mask:0xf bank_mask:0xf bound_ctrl:1
	s_nop 1
	v_add_u32_dpp v12, v12, v12 row_ror:1 row_mask:0xf bank_mask:0xf bound_ctrl:1
	s_nop 0
	v_readlane_b32 s6, v12, 0
	v_readlane_b32 s7, v12, 16
	v_readlane_b32 s8, v12, 32
	v_readlane_b32 s9, v12, 48
	s_add_i32 s6, s6, s7
	s_add_i32 s8, s8, s9
	s_add_i32 s6, s6, s57
	s_add_i32 s8, s6, s8
	s_cmpk_eq_i32 s8, 0x100
	s_cbranch_scc1 .Lrdx_eq
	s_cmpk_lt_i32 s8, 0x100
	s_cselect_b32 s6, -1, 0
	s_cselect_b32 s57, s8, s57
	s_xor_b32 s59, s58, s6
	v_bitop3_b32 v7, v7, v144, s59 bitop3:0x60
	v_bitop3_b32 v3, v3, v8, s6 bitop3:0xf8
	v_bitop3_b32 v8, v7, v142, s58 bitop3:0x60
	v_bcnt_u32_b32 v12, v8, 0
	s_nop 1
	v_add_u32_dpp v12, v12, v12 row_ror:8 row_mask:0xf bank_mask:0xf bound_ctrl:1
	s_nop 1
	v_add_u32_dpp v12, v12, v12 row_ror:4 row_mask:0xf bank_mask:0xf bound_ctrl:1
	s_nop 1
	v_add_u32_dpp v12, v12, v12 row_ror:2 row_mask:0xf bank_mask:0xf bound_ctrl:1
	s_nop 1
	v_add_u32_dpp v12, v12, v12 row_ror:1 row_mask:0xf bank_mask:0xf bound_ctrl:1
	s_nop 0
	v_readlane_b32 s6, v12, 0
	v_readlane_b32 s7, v12, 16
	v_readlane_b32 s8, v12, 32
	v_readlane_b32 s9, v12, 48
	s_add_i32 s6, s6, s7
	s_add_i32 s8, s8, s9
	s_add_i32 s6, s6, s57
	s_add_i32 s8, s6, s8
	s_cmpk_eq_i32 s8, 0x100
	s_cbranch_scc1 .Lrdx_eq
	s_cmpk_lt_i32 s8, 0x100
	s_cselect_b32 s6, -1, 0
	s_cselect_b32 s57, s8, s57
	s_xor_b32 s59, s58, s6
	v_bitop3_b32 v7, v7, v142, s59 bitop3:0x60
	v_bitop3_b32 v3, v3, v8, s6 bitop3:0xf8
	v_bitop3_b32 v8, v7, v140, s58 bitop3:0x60
	v_bcnt_u32_b32 v12, v8, 0
	s_nop 1
	v_add_u32_dpp v12, v12, v12 row_ror:8 row_mask:0xf bank_mask:0xf bound_ctrl:1
	s_nop 1
	v_add_u32_dpp v12, v12, v12 row_ror:4 row_mask:0xf bank_mask:0xf bound_ctrl:1
	s_nop 1
	v_add_u32_dpp v12, v12, v12 row_ror:2 row_mask:0xf bank_mask:0xf bound_ctrl:1
	s_nop 1
	v_add_u32_dpp v12, v12, v12 row_ror:1 row_mask:0xf bank_mask:0xf bound_ctrl:1
	s_nop 0
	v_readlane_b32 s6, v12, 0
	v_readlane_b32 s7, v12, 16
	v_readlane_b32 s8, v12, 32
	v_readlane_b32 s9, v12, 48
	s_add_i32 s6, s6, s7
	s_add_i32 s8, s8, s9
	s_add_i32 s6, s6, s57
	s_add_i32 s8, s6, s8
	s_cmpk_eq_i32 s8, 0x100
	s_cbranch_scc1 .Lrdx_eq
	s_cmpk_lt_i32 s8, 0x100
	s_cselect_b32 s6, -1, 0
	s_cselect_b32 s57, s8, s57
	s_xor_b32 s59, s58, s6
	v_bitop3_b32 v7, v7, v140, s59 bitop3:0x60
	v_bitop3_b32 v3, v3, v8, s6 bitop3:0xf8
	v_bitop3_b32 v8, v7, v138, s58 bitop3:0x60
	v_bcnt_u32_b32 v12, v8, 0
	s_nop 1
	v_add_u32_dpp v12, v12, v12 row_ror:8 row_mask:0xf bank_mask:0xf bound_ctrl:1
	s_nop 1
	v_add_u32_dpp v12, v12, v12 row_ror:4 row_mask:0xf bank_mask:0xf bound_ctrl:1
	s_nop 1
	v_add_u32_dpp v12, v12, v12 row_ror:2 row_mask:0xf bank_mask:0xf bound_ctrl:1
	s_nop 1
	v_add_u32_dpp v12, v12, v12 row_ror:1 row_mask:0xf bank_mask:0xf bound_ctrl:1
	s_nop 0
	v_readlane_b32 s6, v12, 0
	v_readlane_b32 s7, v12, 16
	v_readlane_b32 s8, v12, 32
	v_readlane_b32 s9, v12, 48
	s_add_i32 s6, s6, s7
	s_add_i32 s8, s8, s9
	s_add_i32 s6, s6, s57
	s_add_i32 s8, s6, s8
	s_cmpk_eq_i32 s8, 0x100
	s_cbranch_scc1 .Lrdx_eq
	s_cmpk_lt_i32 s8, 0x100
	s_cselect_b32 s6, -1, 0
	s_cselect_b32 s57, s8, s57
	s_xor_b32 s59, s58, s6
	v_bitop3_b32 v7, v7, v138, s59 bitop3:0x60
	v_bitop3_b32 v3, v3, v8, s6 bitop3:0xf8
	v_bitop3_b32 v8, v7, v136, s58 bitop3:0x60
	v_bcnt_u32_b32 v12, v8, 0
	s_nop 1
	v_add_u32_dpp v12, v12, v12 row_ror:8 row_mask:0xf bank_mask:0xf bound_ctrl:1
	s_nop 1
	v_add_u32_dpp v12, v12, v12 row_ror:4 row_mask:0xf bank_mask:0xf bound_ctrl:1
	s_nop 1
	v_add_u32_dpp v12, v12, v12 row_ror:2 row_mask:0xf bank_mask:0xf bound_ctrl:1
	s_nop 1
	v_add_u32_dpp v12, v12, v12 row_ror:1 row_mask:0xf bank_mask:0xf bound_ctrl:1
	s_nop 0
	v_readlane_b32 s6, v12, 0
	v_readlane_b32 s7, v12, 16
	v_readlane_b32 s8, v12, 32
	v_readlane_b32 s9, v12, 48
	s_add_i32 s6, s6, s7
	s_add_i32 s8, s8, s9
	s_add_i32 s6, s6, s57
	s_add_i32 s8, s6, s8
	s_cmpk_eq_i32 s8, 0x100
	s_cbranch_scc1 .Lrdx_eq
	s_cmpk_lt_i32 s8, 0x100
	s_cselect_b32 s6, -1, 0
	s_cselect_b32 s57, s8, s57
	s_xor_b32 s59, s58, s6
	v_bitop3_b32 v7, v7, v136, s59 bitop3:0x60
	v_bitop3_b32 v3, v3, v8, s6 bitop3:0xf8
	v_bitop3_b32 v8, v7, v134, s58 bitop3:0x60
	v_bcnt_u32_b32 v12, v8, 0
	s_nop 1
	v_add_u32_dpp v12, v12, v12 row_ror:8 row_mask:0xf bank_mask:0xf bound_ctrl:1
	s_nop 1
	v_add_u32_dpp v12, v12, v12 row_ror:4 row_mask:0xf bank_mask:0xf bound_ctrl:1
	s_nop 1
	v_add_u32_dpp v12, v12, v12 row_ror:2 row_mask:0xf bank_mask:0xf bound_ctrl:1
	s_nop 1
	v_add_u32_dpp v12, v12, v12 row_ror:1 row_mask:0xf bank_mask:0xf bound_ctrl:1
	s_nop 0
	v_readlane_b32 s6, v12, 0
	v_readlane_b32 s7, v12, 16
	v_readlane_b32 s8, v12, 32
	v_readlane_b32 s9, v12, 48
	s_add_i32 s6, s6, s7
	s_add_i32 s8, s8, s9
	s_add_i32 s6, s6, s57
	s_add_i32 s8, s6, s8
	s_cmpk_eq_i32 s8, 0x100
	s_cbranch_scc1 .Lrdx_eq
	s_cmpk_lt_i32 s8, 0x100
	s_cselect_b32 s6, -1, 0
	s_cselect_b32 s57, s8, s57
	s_xor_b32 s59, s58, s6
	v_bitop3_b32 v7, v7, v134, s59 bitop3:0x60
	v_bitop3_b32 v3, v3, v8, s6 bitop3:0xf8
	v_bitop3_b32 v8, v7, v132, s58 bitop3:0x60
	v_bcnt_u32_b32 v12, v8, 0
	s_nop 1
	v_add_u32_dpp v12, v12, v12 row_ror:8 row_mask:0xf bank_mask:0xf bound_ctrl:1
	s_nop 1
	v_add_u32_dpp v12, v12, v12 row_ror:4 row_mask:0xf bank_mask:0xf bound_ctrl:1
	s_nop 1
	v_add_u32_dpp v12, v12, v12 row_ror:2 row_mask:0xf bank_mask:0xf bound_ctrl:1
	s_nop 1
	v_add_u32_dpp v12, v12, v12 row_ror:1 row_mask:0xf bank_mask:0xf bound_ctrl:1
	s_nop 0
	v_readlane_b32 s6, v12, 0
	v_readlane_b32 s7, v12, 16
	v_readlane_b32 s8, v12, 32
	v_readlane_b32 s9, v12, 48
	s_add_i32 s6, s6, s7
	s_add_i32 s8, s8, s9
	s_add_i32 s6, s6, s57
	s_add_i32 s8, s6, s8
	s_cmpk_eq_i32 s8, 0x100
	s_cbranch_scc1 .Lrdx_eq
	s_cmpk_lt_i32 s8, 0x100
	s_cselect_b32 s6, -1, 0
	s_cselect_b32 s57, s8, s57
	s_xor_b32 s59, s58, s6
	v_bitop3_b32 v7, v7, v132, s59 bitop3:0x60
	v_bitop3_b32 v3, v3, v8, s6 bitop3:0xf8
	v_bitop3_b32 v8, v7, v130, s58 bitop3:0x60
	v_bcnt_u32_b32 v12, v8, 0
	s_nop 1
	v_add_u32_dpp v12, v12, v12 row_ror:8 row_mask:0xf bank_mask:0xf bound_ctrl:1
	s_nop 1
	v_add_u32_dpp v12, v12, v12 row_ror:4 row_mask:0xf bank_mask:0xf bound_ctrl:1
	s_nop 1
	v_add_u32_dpp v12, v12, v12 row_ror:2 row_mask:0xf bank_mask:0xf bound_ctrl:1
	s_nop 1
	v_add_u32_dpp v12, v12, v12 row_ror:1 row_mask:0xf bank_mask:0xf bound_ctrl:1
	s_nop 0
	v_readlane_b32 s6, v12, 0
	v_readlane_b32 s7, v12, 16
	v_readlane_b32 s8, v12, 32
	v_readlane_b32 s9, v12, 48
	s_add_i32 s6, s6, s7
	s_add_i32 s8, s8, s9
	s_add_i32 s6, s6, s57
	s_add_i32 s8, s6, s8
	s_cmpk_eq_i32 s8, 0x100
	s_cbranch_scc1 .Lrdx_eq
	s_cmpk_lt_i32 s8, 0x100
	s_cselect_b32 s6, -1, 0
	s_cselect_b32 s57, s8, s57
	s_xor_b32 s59, s58, s6
	v_bitop3_b32 v7, v7, v130, s59 bitop3:0x60
	v_bitop3_b32 v3, v3, v8, s6 bitop3:0xf8
	v_bitop3_b32 v8, v7, v128, s58 bitop3:0x60
	v_bcnt_u32_b32 v12, v8, 0
	s_nop 1
	v_add_u32_dpp v12, v12, v12 row_ror:8 row_mask:0xf bank_mask:0xf bound_ctrl:1
	s_nop 1
	v_add_u32_dpp v12, v12, v12 row_ror:4 row_mask:0xf bank_mask:0xf bound_ctrl:1
	s_nop 1
	v_add_u32_dpp v12, v12, v12 row_ror:2 row_mask:0xf bank_mask:0xf bound_ctrl:1
	s_nop 1
	v_add_u32_dpp v12, v12, v12 row_ror:1 row_mask:0xf bank_mask:0xf bound_ctrl:1
	s_nop 0
	v_readlane_b32 s6, v12, 0
	v_readlane_b32 s7, v12, 16
	v_readlane_b32 s8, v12, 32
	v_readlane_b32 s9, v12, 48
	s_add_i32 s6, s6, s7
	s_add_i32 s8, s8, s9
	s_add_i32 s6, s6, s57
	s_add_i32 s8, s6, s8
	s_cmpk_eq_i32 s8, 0x100
	s_cbranch_scc1 .Lrdx_eq
	s_cmpk_lt_i32 s8, 0x100
	s_cselect_b32 s6, -1, 0
	s_cselect_b32 s57, s8, s57
	s_xor_b32 s59, s58, s6
	v_bitop3_b32 v7, v7, v128, s59 bitop3:0x60
	v_bitop3_b32 v3, v3, v8, s6 bitop3:0xf8
	v_bitop3_b32 v8, v7, v126, s58 bitop3:0x60
	v_bcnt_u32_b32 v12, v8, 0
	s_nop 1
	v_add_u32_dpp v12, v12, v12 row_ror:8 row_mask:0xf bank_mask:0xf bound_ctrl:1
	s_nop 1
	v_add_u32_dpp v12, v12, v12 row_ror:4 row_mask:0xf bank_mask:0xf bound_ctrl:1
	s_nop 1
	v_add_u32_dpp v12, v12, v12 row_ror:2 row_mask:0xf bank_mask:0xf bound_ctrl:1
	s_nop 1
	v_add_u32_dpp v12, v12, v12 row_ror:1 row_mask:0xf bank_mask:0xf bound_ctrl:1
	s_nop 0
	v_readlane_b32 s6, v12, 0
	v_readlane_b32 s7, v12, 16
	v_readlane_b32 s8, v12, 32
	v_readlane_b32 s9, v12, 48
	s_add_i32 s6, s6, s7
	s_add_i32 s8, s8, s9
	s_add_i32 s6, s6, s57
	s_add_i32 s8, s6, s8
	s_cmpk_eq_i32 s8, 0x100
	s_cbranch_scc1 .Lrdx_eq
	s_cmpk_lt_i32 s8, 0x100
	s_cselect_b32 s6, -1, 0
	s_cselect_b32 s57, s8, s57
	s_xor_b32 s59, s58, s6
	v_bitop3_b32 v7, v7, v126, s59 bitop3:0x60
	v_bitop3_b32 v3, v3, v8, s6 bitop3:0xf8
	v_bitop3_b32 v8, v7, v124, s58 bitop3:0x60
	v_bcnt_u32_b32 v12, v8, 0
	s_nop 1
	v_add_u32_dpp v12, v12, v12 row_ror:8 row_mask:0xf bank_mask:0xf bound_ctrl:1
	s_nop 1
	v_add_u32_dpp v12, v12, v12 row_ror:4 row_mask:0xf bank_mask:0xf bound_ctrl:1
	s_nop 1
	v_add_u32_dpp v12, v12, v12 row_ror:2 row_mask:0xf bank_mask:0xf bound_ctrl:1
	s_nop 1
	v_add_u32_dpp v12, v12, v12 row_ror:1 row_mask:0xf bank_mask:0xf bound_ctrl:1
	s_nop 0
	v_readlane_b32 s6, v12, 0
	v_readlane_b32 s7, v12, 16
	v_readlane_b32 s8, v12, 32
	v_readlane_b32 s9, v12, 48
	s_add_i32 s6, s6, s7
	s_add_i32 s8, s8, s9
	s_add_i32 s6, s6, s57
	s_add_i32 s8, s6, s8
	s_cmpk_eq_i32 s8, 0x100
	s_cbranch_scc1 .Lrdx_eq
	s_cmpk_lt_i32 s8, 0x100
	s_cselect_b32 s6, -1, 0
	s_cselect_b32 s57, s8, s57
	s_xor_b32 s59, s58, s6
	v_bitop3_b32 v7, v7, v124, s59 bitop3:0x60
	v_bitop3_b32 v3, v3, v8, s6 bitop3:0xf8
	v_bitop3_b32 v8, v7, v122, s58 bitop3:0x60
	v_bcnt_u32_b32 v12, v8, 0
	s_nop 1
	v_add_u32_dpp v12, v12, v12 row_ror:8 row_mask:0xf bank_mask:0xf bound_ctrl:1
	s_nop 1
	v_add_u32_dpp v12, v12, v12 row_ror:4 row_mask:0xf bank_mask:0xf bound_ctrl:1
	s_nop 1
	v_add_u32_dpp v12, v12, v12 row_ror:2 row_mask:0xf bank_mask:0xf bound_ctrl:1
	s_nop 1
	v_add_u32_dpp v12, v12, v12 row_ror:1 row_mask:0xf bank_mask:0xf bound_ctrl:1
	s_nop 0
	v_readlane_b32 s6, v12, 0
	v_readlane_b32 s7, v12, 16
	v_readlane_b32 s8, v12, 32
	v_readlane_b32 s9, v12, 48
	s_add_i32 s6, s6, s7
	s_add_i32 s8, s8, s9
	s_add_i32 s6, s6, s57
	s_add_i32 s8, s6, s8
	s_cmpk_eq_i32 s8, 0x100
	s_cbranch_scc1 .Lrdx_eq
	s_cmpk_lt_i32 s8, 0x100
	s_cselect_b32 s6, -1, 0
	s_cselect_b32 s57, s8, s57
	s_xor_b32 s59, s58, s6
	v_bitop3_b32 v7, v7, v122, s59 bitop3:0x60
	v_bitop3_b32 v3, v3, v8, s6 bitop3:0xf8
	v_bitop3_b32 v8, v7, v120, s58 bitop3:0x60
	v_bcnt_u32_b32 v12, v8, 0
	s_nop 1
	v_add_u32_dpp v12, v12, v12 row_ror:8 row_mask:0xf bank_mask:0xf bound_ctrl:1
	s_nop 1
	v_add_u32_dpp v12, v12, v12 row_ror:4 row_mask:0xf bank_mask:0xf bound_ctrl:1
	s_nop 1
	v_add_u32_dpp v12, v12, v12 row_ror:2 row_mask:0xf bank_mask:0xf bound_ctrl:1
	s_nop 1
	v_add_u32_dpp v12, v12, v12 row_ror:1 row_mask:0xf bank_mask:0xf bound_ctrl:1
	s_nop 0
	v_readlane_b32 s6, v12, 0
	v_readlane_b32 s7, v12, 16
	v_readlane_b32 s8, v12, 32
	v_readlane_b32 s9, v12, 48
	s_add_i32 s6, s6, s7
	s_add_i32 s8, s8, s9
	s_add_i32 s6, s6, s57
	s_add_i32 s8, s6, s8
	s_cmpk_eq_i32 s8, 0x100
	s_cbranch_scc1 .Lrdx_eq
	s_cmpk_lt_i32 s8, 0x100
	s_cselect_b32 s6, -1, 0
	s_cselect_b32 s57, s8, s57
	s_xor_b32 s59, s58, s6
	v_bitop3_b32 v7, v7, v120, s59 bitop3:0x60
	v_bitop3_b32 v3, v3, v8, s6 bitop3:0xf8
	v_bitop3_b32 v8, v7, v118, s58 bitop3:0x60
	v_bcnt_u32_b32 v12, v8, 0
	s_nop 1
	v_add_u32_dpp v12, v12, v12 row_ror:8 row_mask:0xf bank_mask:0xf bound_ctrl:1
	s_nop 1
	v_add_u32_dpp v12, v12, v12 row_ror:4 row_mask:0xf bank_mask:0xf bound_ctrl:1
	s_nop 1
	v_add_u32_dpp v12, v12, v12 row_ror:2 row_mask:0xf bank_mask:0xf bound_ctrl:1
	s_nop 1
	v_add_u32_dpp v12, v12, v12 row_ror:1 row_mask:0xf bank_mask:0xf bound_ctrl:1
	s_nop 0
	v_readlane_b32 s6, v12, 0
	v_readlane_b32 s7, v12, 16
	v_readlane_b32 s8, v12, 32
	v_readlane_b32 s9, v12, 48
	s_add_i32 s6, s6, s7
	s_add_i32 s8, s8, s9
	s_add_i32 s6, s6, s57
	s_add_i32 s8, s6, s8
	s_cmpk_eq_i32 s8, 0x100
	s_cbranch_scc1 .Lrdx_eq
	s_cmpk_lt_i32 s8, 0x100
	s_cselect_b32 s6, -1, 0
	s_cselect_b32 s57, s8, s57
	s_xor_b32 s59, s58, s6
	v_bitop3_b32 v7, v7, v118, s59 bitop3:0x60
	v_bitop3_b32 v3, v3, v8, s6 bitop3:0xf8
	v_bitop3_b32 v8, v7, v116, s58 bitop3:0x60
	v_bcnt_u32_b32 v12, v8, 0
	s_nop 1
	v_add_u32_dpp v12, v12, v12 row_ror:8 row_mask:0xf bank_mask:0xf bound_ctrl:1
	s_nop 1
	v_add_u32_dpp v12, v12, v12 row_ror:4 row_mask:0xf bank_mask:0xf bound_ctrl:1
	s_nop 1
	v_add_u32_dpp v12, v12, v12 row_ror:2 row_mask:0xf bank_mask:0xf bound_ctrl:1
	s_nop 1
	v_add_u32_dpp v12, v12, v12 row_ror:1 row_mask:0xf bank_mask:0xf bound_ctrl:1
	s_nop 0
	v_readlane_b32 s6, v12, 0
	v_readlane_b32 s7, v12, 16
	v_readlane_b32 s8, v12, 32
	v_readlane_b32 s9, v12, 48
	s_add_i32 s6, s6, s7
	s_add_i32 s8, s8, s9
	s_add_i32 s6, s6, s57
	s_add_i32 s8, s6, s8
	s_cmpk_eq_i32 s8, 0x100
	s_cbranch_scc1 .Lrdx_eq
	s_cmpk_lt_i32 s8, 0x100
	s_cselect_b32 s6, -1, 0
	s_cselect_b32 s57, s8, s57
	s_xor_b32 s59, s58, s6
	v_bitop3_b32 v7, v7, v116, s59 bitop3:0x60
	v_bitop3_b32 v3, v3, v8, s6 bitop3:0xf8
	v_bitop3_b32 v8, v7, v114, s58 bitop3:0x60
	v_bcnt_u32_b32 v12, v8, 0
	s_nop 1
	v_add_u32_dpp v12, v12, v12 row_ror:8 row_mask:0xf bank_mask:0xf bound_ctrl:1
	s_nop 1
	v_add_u32_dpp v12, v12, v12 row_ror:4 row_mask:0xf bank_mask:0xf bound_ctrl:1
	s_nop 1
	v_add_u32_dpp v12, v12, v12 row_ror:2 row_mask:0xf bank_mask:0xf bound_ctrl:1
	s_nop 1
	v_add_u32_dpp v12, v12, v12 row_ror:1 row_mask:0xf bank_mask:0xf bound_ctrl:1
	s_nop 0
	v_readlane_b32 s6, v12, 0
	v_readlane_b32 s7, v12, 16
	v_readlane_b32 s8, v12, 32
	v_readlane_b32 s9, v12, 48
	s_add_i32 s6, s6, s7
	s_add_i32 s8, s8, s9
	s_add_i32 s6, s6, s57
	s_add_i32 s8, s6, s8
	s_cmpk_eq_i32 s8, 0x100
	s_cbranch_scc1 .Lrdx_eq
	s_cmpk_lt_i32 s8, 0x100
	s_cselect_b32 s6, -1, 0
	s_cselect_b32 s57, s8, s57
	s_xor_b32 s59, s58, s6
	v_bitop3_b32 v7, v7, v114, s59 bitop3:0x60
	v_bitop3_b32 v3, v3, v8, s6 bitop3:0xf8
	v_bitop3_b32 v8, v7, v112, s58 bitop3:0x60
	v_bcnt_u32_b32 v12, v8, 0
	s_nop 1
	v_add_u32_dpp v12, v12, v12 row_ror:8 row_mask:0xf bank_mask:0xf bound_ctrl:1
	s_nop 1
	v_add_u32_dpp v12, v12, v12 row_ror:4 row_mask:0xf bank_mask:0xf bound_ctrl:1
	s_nop 1
	v_add_u32_dpp v12, v12, v12 row_ror:2 row_mask:0xf bank_mask:0xf bound_ctrl:1
	s_nop 1
	v_add_u32_dpp v12, v12, v12 row_ror:1 row_mask:0xf bank_mask:0xf bound_ctrl:1
	s_nop 0
	v_readlane_b32 s6, v12, 0
	v_readlane_b32 s7, v12, 16
	v_readlane_b32 s8, v12, 32
	v_readlane_b32 s9, v12, 48
	s_add_i32 s6, s6, s7
	s_add_i32 s8, s8, s9
	s_add_i32 s6, s6, s57
	s_add_i32 s8, s6, s8
	s_cmpk_eq_i32 s8, 0x100
	s_cbranch_scc1 .Lrdx_eq
	s_cmpk_lt_i32 s8, 0x100
	s_cselect_b32 s6, -1, 0
	s_cselect_b32 s57, s8, s57
	s_xor_b32 s59, s58, s6
	v_bitop3_b32 v7, v7, v112, s59 bitop3:0x60
	v_bitop3_b32 v3, v3, v8, s6 bitop3:0xf8
	v_bitop3_b32 v8, v7, v110, s58 bitop3:0x60
	v_bcnt_u32_b32 v12, v8, 0
	s_nop 1
	v_add_u32_dpp v12, v12, v12 row_ror:8 row_mask:0xf bank_mask:0xf bound_ctrl:1
	s_nop 1
	v_add_u32_dpp v12, v12, v12 row_ror:4 row_mask:0xf bank_mask:0xf bound_ctrl:1
	s_nop 1
	v_add_u32_dpp v12, v12, v12 row_ror:2 row_mask:0xf bank_mask:0xf bound_ctrl:1
	s_nop 1
	v_add_u32_dpp v12, v12, v12 row_ror:1 row_mask:0xf bank_mask:0xf bound_ctrl:1
	s_nop 0
	v_readlane_b32 s6, v12, 0
	v_readlane_b32 s7, v12, 16
	v_readlane_b32 s8, v12, 32
	v_readlane_b32 s9, v12, 48
	s_add_i32 s6, s6, s7
	s_add_i32 s8, s8, s9
	s_add_i32 s6, s6, s57
	s_add_i32 s8, s6, s8
	s_cmpk_eq_i32 s8, 0x100
	s_cbranch_scc1 .Lrdx_eq
	s_cmpk_lt_i32 s8, 0x100
	s_cselect_b32 s6, -1, 0
	s_cselect_b32 s57, s8, s57
	s_xor_b32 s59, s58, s6
	v_bitop3_b32 v7, v7, v110, s59 bitop3:0x60
	v_bitop3_b32 v3, v3, v8, s6 bitop3:0xf8
	v_bitop3_b32 v8, v7, v108, s58 bitop3:0x60
	v_bcnt_u32_b32 v12, v8, 0
	s_nop 1
	v_add_u32_dpp v12, v12, v12 row_ror:8 row_mask:0xf bank_mask:0xf bound_ctrl:1
	s_nop 1
	v_add_u32_dpp v12, v12, v12 row_ror:4 row_mask:0xf bank_mask:0xf bound_ctrl:1
	s_nop 1
	v_add_u32_dpp v12, v12, v12 row_ror:2 row_mask:0xf bank_mask:0xf bound_ctrl:1
	s_nop 1
	v_add_u32_dpp v12, v12, v12 row_ror:1 row_mask:0xf bank_mask:0xf bound_ctrl:1
	s_nop 0
	v_readlane_b32 s6, v12, 0
	v_readlane_b32 s7, v12, 16
	v_readlane_b32 s8, v12, 32
	v_readlane_b32 s9, v12, 48
	s_add_i32 s6, s6, s7
	s_add_i32 s8, s8, s9
	s_add_i32 s6, s6, s57
	s_add_i32 s8, s6, s8
	s_cmpk_eq_i32 s8, 0x100
	s_cbranch_scc1 .Lrdx_eq
	s_cmpk_lt_i32 s8, 0x100
	s_cselect_b32 s6, -1, 0
	s_cselect_b32 s57, s8, s57
	s_xor_b32 s59, s58, s6
	v_bitop3_b32 v7, v7, v108, s59 bitop3:0x60
	v_bitop3_b32 v3, v3, v8, s6 bitop3:0xf8
	s_branch .LBB0_1099

.LBB0_1141:
	s_waitcnt lgkmcnt(0)
	s_add_i32 s6, s18, s12
	v_lshl_add_u32 v0, v96, 2, s40
	s_ashr_i32 s7, s6, 31
	ds_read_b128 v[0:3], v0
	s_lshl_b64 s[6:7], s[6:7], 10
	s_add_u32 s6, s24, s6
	s_addc_u32 s7, s25, s7
	v_lshl_add_u64 v[4:5], v[96:97], 2, s[6:7]
	s_waitcnt lgkmcnt(0)
	global_store_dwordx4 v[4:5], v[0:3], off
	s_barrier
	v_mov_b32_e32 v0, s3
	s_branch .Lsel_next
